# weight transpose phase: hand-written tile loop, 4 tiles (32 loads per thread) in flight per iteration
# speedup vs baseline: 1.0020x; 1.0020x over previous
; __device__ __forceinline__ void tr_tile(const int tid, float* tile, const float* src, int ld, int k0, int j0, bool remap, bf16_t* dst, int ldd, int kd0) {
;     const int jj = tid & 63, kq = tid >> 6;
;     const int col = remap ? win_col(j0 + jj) : (j0 + jj);
; #pragma unroll
;     for (int i = 0; i < 8; ++i) { const int kk = kq + 8 * i; tile[kk * 65 + jj] = col >= 0 ? src[(size_t)(k0 + kk) * ld + col] : 0.f; }
; __device__ __forceinline__ void conv_phase(unsigned char* lds, const Params& p, int l, const int tid) {
;     ...
;     for (int it = blockIdx.x; it < nmod + NT_IN + NT_P + NT_O; it += gridDim.x) {
;         int id = it;
;         if (id < nmod) { mod_item(tid, tile, p, id); continue; }
;         id -= nmod;
;         if (id < NT_IN) { const int kt = id & 31, jt = id >> 5; tr_tile(tid, tile, p.in[11] + (size_t)l * 2048 * IND, IND, kt * 64, jt * 64, true, (bf16_t*)(p.ws + WS_WIN), 2048, kt * 64); continue; }
;         id -= NT_IN;
;         if (id < NT_P) { const int kt = id & 31, jt = id >> 5;
;             const float* src = kt < 16 ? p.in[19] + (size_t)l * 1024 * 2048 : p.in[20] + (size_t)l * 1024 * 2048;
;             tr_tile(tid, tile, src, 2048, (kt & 15) * 64, jt * 64, false, (bf16_t*)(p.ws + WS_WP), 2048, kt * 64); continue; }
;         id -= NT_P;
;         { const int kt = id & 31, jt = id >> 5; tr_tile(tid, tile, p.in[21] + (size_t)l * 2048 * 2048, 2048, kt * 64, jt * 64, false, (bf16_t*)(p.ws + WS_WO), 2048, kt * 64); }
.LBB0_803:
	s_cmp_ge_i32 s20, s16
	s_mov_b64 s[4:5], -1
	s_cbranch_scc0 .LBB0_827
	v_readlane_b32 s50, v246, 52
	v_readlane_b32 s51, v246, 53
	v_and_b32_e32 v40, 63, v188
	v_lshrrev_b32_e32 v41, 6, v188
	v_lshrrev_b32_e32 v42, 3, v188
	v_and_b32_e32 v43, 7, v188
	v_mul_u32_u24_e32 v44, 0x41, v41
	v_add_u32_e32 v44, v44, v40
	v_lshlrev_b32_e32 v44, 2, v44
	v_mul_u32_u24_e32 v45, 0x208, v43
	v_add_u32_e32 v45, v45, v42
	v_lshlrev_b32_e32 v45, 2, v45
	v_lshlrev_b32_e32 v46, 12, v42
	v_lshl_add_u32 v46, v43, 4, v46
	v_add_u32_e32 v144, 0x0, v45
	v_add_u32_e32 v145, 0x400, v45
	v_add_u32_e32 v146, 0x4100, v45
	v_add_u32_e32 v147, 0x4500, v45
	v_add_u32_e32 v148, 0x8200, v45
	v_add_u32_e32 v149, 0x8600, v45
	v_add_u32_e32 v150, 0xc300, v45
	v_add_u32_e32 v151, 0xc700, v45
.Lcv_loop:
	s_mov_b32 s46, 0
	s_mov_b32 s21, s20
	s_cmp_ge_i32 s21, s17
	s_cbranch_scc1 .Lcv_skip0
	s_or_b32 s46, s46, 1
	s_sub_i32 s24, s21, s16
	s_and_b32 s25, s24, 31
	s_lshr_b32 s26, s24, 5
	s_mov_b64 s[28:29], s[12:13]
	s_mov_b32 s27, 0xc040
	s_mov_b64 s[30:31], s[50:51]
	s_mov_b64 s[34:35], -1
	s_lshl_b32 s36, s25, 6
	s_mov_b32 s37, s36
	s_cmpk_gt_u32 s24, 0x187f
	s_cbranch_scc0 .Lcv_k0
	s_add_i32 s37, s24, 0xffffe780
	s_and_b32 s25, s37, 31
	s_lshr_b32 s26, s37, 5
	s_movk_i32 s27, 0x2000
	s_mov_b64 s[34:35], 0
	s_lshl_b32 s36, s25, 6
	s_mov_b32 s37, s36
	s_cmpk_gt_u32 s24, 0x1c7f
	s_cbranch_scc1 .Lcv_o0
	s_cmp_lt_u32 s25, 16
	s_cselect_b32 s28, s84, s86
	s_cselect_b32 s29, s85, s87
	s_add_u32 s28, s28, s2
	s_addc_u32 s29, s29, s3
	s_mov_b64 s[30:31], s[10:11]
	s_and_b32 s37, s25, 15
	s_lshl_b32 s37, s37, 6
	s_branch .Lcv_k0
.Lcv_o0:
	s_add_i32 s26, s26, -32
	s_mov_b64 s[28:29], s[6:7]
	s_mov_b64 s[30:31], s[8:9]
.Lcv_k0:
	s_mul_i32 s40, s37, s27
	s_add_u32 s28, s28, s40
	s_addc_u32 s29, s29, 0
	s_lshl_b32 s40, s36, 1
	s_add_u32 s30, s30, s40
	s_addc_u32 s31, s31, 0
	s_lshl_b32 s41, s26, 6
	s_lshl_b32 s42, s27, 3
	s_mov_b32 s43, 0
	v_add_u32_e32 v0, s41, v40
	v_add_u32_e32 v1, 16, v0
	v_cmp_gt_u32_e32 vcc, 0x1000, v0
	v_add_u32_e32 v2, 0xffffe000, v0
	v_mul_lo_u32 v3, v41, s27
	v_cndmask_b32_e32 v1, v1, v0, vcc
	v_cmp_gt_u32_e32 vcc, 0x3000, v0
	s_nop 1
	v_cndmask_b32_e32 v1, v2, v1, vcc
	v_cmp_gt_u32_e32 vcc, 0x3010, v0
	s_nop 1
	v_cndmask_b32_e32 v1, -1, v1, vcc
	v_cndmask_b32_e64 v1, v0, v1, s[34:35]
	v_lshl_add_u32 v136, v1, 2, v3
	v_lshl_add_u64 v[2:3], s[28:29], 0, v[136:137]
	v_cmp_le_i32_e32 vcc, 0, v1
	v_mov_b32_e32 v48, 0
	v_mov_b32_e32 v49, 0
	v_mov_b32_e32 v50, 0
	v_mov_b32_e32 v51, 0
	v_mov_b32_e32 v52, 0
	v_mov_b32_e32 v53, 0
	v_mov_b32_e32 v54, 0
	v_mov_b32_e32 v55, 0
	s_and_saveexec_b64 s[44:45], vcc
	global_load_dword v48, v[2:3], off
	v_lshl_add_u64 v[2:3], v[2:3], 0, s[42:43]
	global_load_dword v49, v[2:3], off
	v_lshl_add_u64 v[2:3], v[2:3], 0, s[42:43]
	global_load_dword v50, v[2:3], off
	v_lshl_add_u64 v[2:3], v[2:3], 0, s[42:43]
	global_load_dword v51, v[2:3], off
	v_lshl_add_u64 v[2:3], v[2:3], 0, s[42:43]
	global_load_dword v52, v[2:3], off
	v_lshl_add_u64 v[2:3], v[2:3], 0, s[42:43]
	global_load_dword v53, v[2:3], off
	v_lshl_add_u64 v[2:3], v[2:3], 0, s[42:43]
	global_load_dword v54, v[2:3], off
	v_lshl_add_u64 v[2:3], v[2:3], 0, s[42:43]
	global_load_dword v55, v[2:3], off
	s_mov_b64 exec, s[44:45]
	s_lshl_b32 s40, s41, 12
	v_add_u32_e32 v136, s40, v46
	v_lshl_add_u64 v[112:113], s[30:31], 0, v[136:137]
.Lcv_skip0:
	s_add_i32 s21, s21, s80
	s_cmp_ge_i32 s21, s17
	s_cbranch_scc1 .Lcv_skip1
	s_or_b32 s46, s46, 2
	s_sub_i32 s24, s21, s16
	s_and_b32 s25, s24, 31
	s_lshr_b32 s26, s24, 5
	s_mov_b64 s[28:29], s[12:13]
	s_mov_b32 s27, 0xc040
	s_mov_b64 s[30:31], s[50:51]
	s_mov_b64 s[34:35], -1
	s_lshl_b32 s36, s25, 6
	s_mov_b32 s37, s36
	s_cmpk_gt_u32 s24, 0x187f
	s_cbranch_scc0 .Lcv_k1
	s_add_i32 s37, s24, 0xffffe780
	s_and_b32 s25, s37, 31
	s_lshr_b32 s26, s37, 5
	s_movk_i32 s27, 0x2000
	s_mov_b64 s[34:35], 0
	s_lshl_b32 s36, s25, 6
	s_mov_b32 s37, s36
	s_cmpk_gt_u32 s24, 0x1c7f
	s_cbranch_scc1 .Lcv_o1
	s_cmp_lt_u32 s25, 16
	s_cselect_b32 s28, s84, s86
	s_cselect_b32 s29, s85, s87
	s_add_u32 s28, s28, s2
	s_addc_u32 s29, s29, s3
	s_mov_b64 s[30:31], s[10:11]
	s_and_b32 s37, s25, 15
	s_lshl_b32 s37, s37, 6
	s_branch .Lcv_k1

; __device__ __forceinline__ void tr_tile(const int tid, float* tile, const float* src, int ld, int k0, int j0, bool remap, bf16_t* dst, int ldd, int kd0) {
;     const int jj = tid & 63, kq = tid >> 6;
;     const int col = remap ? win_col(j0 + jj) : (j0 + jj);
; #pragma unroll
;     for (int i = 0; i < 8; ++i) { const int kk = kq + 8 * i; tile[kk * 65 + jj] = col >= 0 ? src[(size_t)(k0 + kk) * ld + col] : 0.f; }
; __device__ __forceinline__ void conv_phase(unsigned char* lds, const Params& p, int l, const int tid) {
;     ...
;     for (int it = blockIdx.x; it < nmod + NT_IN + NT_P + NT_O; it += gridDim.x) {
;         int id = it;
;         if (id < nmod) { mod_item(tid, tile, p, id); continue; }
;         id -= nmod;
;         if (id < NT_IN) { const int kt = id & 31, jt = id >> 5; tr_tile(tid, tile, p.in[11] + (size_t)l * 2048 * IND, IND, kt * 64, jt * 64, true, (bf16_t*)(p.ws + WS_WIN), 2048, kt * 64); continue; }
;         id -= NT_IN;
;         if (id < NT_P) { const int kt = id & 31, jt = id >> 5;
;             const float* src = kt < 16 ? p.in[19] + (size_t)l * 1024 * 2048 : p.in[20] + (size_t)l * 1024 * 2048;
;             tr_tile(tid, tile, src, 2048, (kt & 15) * 64, jt * 64, false, (bf16_t*)(p.ws + WS_WP), 2048, kt * 64); continue; }
;         id -= NT_P;
;         { const int kt = id & 31, jt = id >> 5; tr_tile(tid, tile, p.in[21] + (size_t)l * 2048 * 2048, 2048, kt * 64, jt * 64, false, (bf16_t*)(p.ws + WS_WO), 2048, kt * 64); }
.Lcv_k1:
	s_mul_i32 s40, s37, s27
	s_add_u32 s28, s28, s40
	s_addc_u32 s29, s29, 0
	s_lshl_b32 s40, s36, 1
	s_add_u32 s30, s30, s40
	s_addc_u32 s31, s31, 0
	s_lshl_b32 s41, s26, 6
	s_lshl_b32 s42, s27, 3
	s_mov_b32 s43, 0
	v_add_u32_e32 v0, s41, v40
	v_add_u32_e32 v1, 16, v0
	v_cmp_gt_u32_e32 vcc, 0x1000, v0
	v_add_u32_e32 v2, 0xffffe000, v0
	v_mul_lo_u32 v3, v41, s27
	v_cndmask_b32_e32 v1, v1, v0, vcc
	v_cmp_gt_u32_e32 vcc, 0x3000, v0
	s_nop 1
	v_cndmask_b32_e32 v1, v2, v1, vcc
	v_cmp_gt_u32_e32 vcc, 0x3010, v0
	s_nop 1
	v_cndmask_b32_e32 v1, -1, v1, vcc
	v_cndmask_b32_e64 v1, v0, v1, s[34:35]
	v_lshl_add_u32 v136, v1, 2, v3
	v_lshl_add_u64 v[2:3], s[28:29], 0, v[136:137]
	v_cmp_le_i32_e32 vcc, 0, v1
	v_mov_b32_e32 v56, 0
	v_mov_b32_e32 v57, 0
	v_mov_b32_e32 v58, 0
	v_mov_b32_e32 v59, 0
	v_mov_b32_e32 v60, 0
	v_mov_b32_e32 v61, 0
	v_mov_b32_e32 v62, 0
	v_mov_b32_e32 v63, 0
	s_and_saveexec_b64 s[44:45], vcc
	global_load_dword v56, v[2:3], off
	v_lshl_add_u64 v[2:3], v[2:3], 0, s[42:43]
	global_load_dword v57, v[2:3], off
	v_lshl_add_u64 v[2:3], v[2:3], 0, s[42:43]
	global_load_dword v58, v[2:3], off
	v_lshl_add_u64 v[2:3], v[2:3], 0, s[42:43]
	global_load_dword v59, v[2:3], off
	v_lshl_add_u64 v[2:3], v[2:3], 0, s[42:43]
	global_load_dword v60, v[2:3], off
	v_lshl_add_u64 v[2:3], v[2:3], 0, s[42:43]
	global_load_dword v61, v[2:3], off
	v_lshl_add_u64 v[2:3], v[2:3], 0, s[42:43]
	global_load_dword v62, v[2:3], off
	v_lshl_add_u64 v[2:3], v[2:3], 0, s[42:43]
	global_load_dword v63, v[2:3], off
	s_mov_b64 exec, s[44:45]
	s_lshl_b32 s40, s41, 12
	v_add_u32_e32 v136, s40, v46
	v_lshl_add_u64 v[114:115], s[30:31], 0, v[136:137]
.Lcv_skip1:
	s_add_i32 s21, s21, s80
	s_cmp_ge_i32 s21, s17
	s_cbranch_scc1 .Lcv_skip2
	s_or_b32 s46, s46, 4
	s_sub_i32 s24, s21, s16
	s_and_b32 s25, s24, 31
	s_lshr_b32 s26, s24, 5
	s_mov_b64 s[28:29], s[12:13]
	s_mov_b32 s27, 0xc040
	s_mov_b64 s[30:31], s[50:51]
	s_mov_b64 s[34:35], -1
	s_lshl_b32 s36, s25, 6
	s_mov_b32 s37, s36
	s_cmpk_gt_u32 s24, 0x187f
	s_cbranch_scc0 .Lcv_k2
	s_add_i32 s37, s24, 0xffffe780
	s_and_b32 s25, s37, 31
	s_lshr_b32 s26, s37, 5
	s_movk_i32 s27, 0x2000
	s_mov_b64 s[34:35], 0
	s_lshl_b32 s36, s25, 6
	s_mov_b32 s37, s36
	s_cmpk_gt_u32 s24, 0x1c7f
	s_cbranch_scc1 .Lcv_o2
	s_cmp_lt_u32 s25, 16
	s_cselect_b32 s28, s84, s86
	s_cselect_b32 s29, s85, s87
	s_add_u32 s28, s28, s2
	s_addc_u32 s29, s29, s3
	s_mov_b64 s[30:31], s[10:11]
	s_and_b32 s37, s25, 15
	s_lshl_b32 s37, s37, 6
	s_branch .Lcv_k2

; __device__ __forceinline__ void tr_tile(const int tid, float* tile, const float* src, int ld, int k0, int j0, bool remap, bf16_t* dst, int ldd, int kd0) {
;     const int jj = tid & 63, kq = tid >> 6;
;     const int col = remap ? win_col(j0 + jj) : (j0 + jj);
; #pragma unroll
;     for (int i = 0; i < 8; ++i) { const int kk = kq + 8 * i; tile[kk * 65 + jj] = col >= 0 ? src[(size_t)(k0 + kk) * ld + col] : 0.f; }
; __device__ __forceinline__ void conv_phase(unsigned char* lds, const Params& p, int l, const int tid) {
;     ...
;     for (int it = blockIdx.x; it < nmod + NT_IN + NT_P + NT_O; it += gridDim.x) {
;         int id = it;
;         if (id < nmod) { mod_item(tid, tile, p, id); continue; }
;         id -= nmod;
;         if (id < NT_IN) { const int kt = id & 31, jt = id >> 5; tr_tile(tid, tile, p.in[11] + (size_t)l * 2048 * IND, IND, kt * 64, jt * 64, true, (bf16_t*)(p.ws + WS_WIN), 2048, kt * 64); continue; }
;         id -= NT_IN;
;         if (id < NT_P) { const int kt = id & 31, jt = id >> 5;
;             const float* src = kt < 16 ? p.in[19] + (size_t)l * 1024 * 2048 : p.in[20] + (size_t)l * 1024 * 2048;
;             tr_tile(tid, tile, src, 2048, (kt & 15) * 64, jt * 64, false, (bf16_t*)(p.ws + WS_WP), 2048, kt * 64); continue; }
;         id -= NT_P;
;         { const int kt = id & 31, jt = id >> 5; tr_tile(tid, tile, p.in[21] + (size_t)l * 2048 * 2048, 2048, kt * 64, jt * 64, false, (bf16_t*)(p.ws + WS_WO), 2048, kt * 64); }
.Lcv_k2:
	s_mul_i32 s40, s37, s27
	s_add_u32 s28, s28, s40
	s_addc_u32 s29, s29, 0
	s_lshl_b32 s40, s36, 1
	s_add_u32 s30, s30, s40
	s_addc_u32 s31, s31, 0
	s_lshl_b32 s41, s26, 6
	s_lshl_b32 s42, s27, 3
	s_mov_b32 s43, 0
	v_add_u32_e32 v0, s41, v40
	v_add_u32_e32 v1, 16, v0
	v_cmp_gt_u32_e32 vcc, 0x1000, v0
	v_add_u32_e32 v2, 0xffffe000, v0
	v_mul_lo_u32 v3, v41, s27
	v_cndmask_b32_e32 v1, v1, v0, vcc
	v_cmp_gt_u32_e32 vcc, 0x3000, v0
	s_nop 1
	v_cndmask_b32_e32 v1, v2, v1, vcc
	v_cmp_gt_u32_e32 vcc, 0x3010, v0
	s_nop 1
	v_cndmask_b32_e32 v1, -1, v1, vcc
	v_cndmask_b32_e64 v1, v0, v1, s[34:35]
	v_lshl_add_u32 v136, v1, 2, v3
	v_lshl_add_u64 v[2:3], s[28:29], 0, v[136:137]
	v_cmp_le_i32_e32 vcc, 0, v1
	v_mov_b32_e32 v64, 0
	v_mov_b32_e32 v65, 0
	v_mov_b32_e32 v66, 0
	v_mov_b32_e32 v67, 0
	v_mov_b32_e32 v68, 0
	v_mov_b32_e32 v69, 0
	v_mov_b32_e32 v70, 0
	v_mov_b32_e32 v71, 0
	s_and_saveexec_b64 s[44:45], vcc
	global_load_dword v64, v[2:3], off
	v_lshl_add_u64 v[2:3], v[2:3], 0, s[42:43]
	global_load_dword v65, v[2:3], off
	v_lshl_add_u64 v[2:3], v[2:3], 0, s[42:43]
	global_load_dword v66, v[2:3], off
	v_lshl_add_u64 v[2:3], v[2:3], 0, s[42:43]
	global_load_dword v67, v[2:3], off
	v_lshl_add_u64 v[2:3], v[2:3], 0, s[42:43]
	global_load_dword v68, v[2:3], off
	v_lshl_add_u64 v[2:3], v[2:3], 0, s[42:43]
	global_load_dword v69, v[2:3], off
	v_lshl_add_u64 v[2:3], v[2:3], 0, s[42:43]
	global_load_dword v70, v[2:3], off
	v_lshl_add_u64 v[2:3], v[2:3], 0, s[42:43]
	global_load_dword v71, v[2:3], off
	s_mov_b64 exec, s[44:45]
	s_lshl_b32 s40, s41, 12
	v_add_u32_e32 v136, s40, v46
	v_lshl_add_u64 v[116:117], s[30:31], 0, v[136:137]
.Lcv_skip2:
	s_add_i32 s21, s21, s80
	s_cmp_ge_i32 s21, s17
	s_cbranch_scc1 .Lcv_skip3
	s_or_b32 s46, s46, 8
	s_sub_i32 s24, s21, s16
	s_and_b32 s25, s24, 31
	s_lshr_b32 s26, s24, 5
	s_mov_b64 s[28:29], s[12:13]
	s_mov_b32 s27, 0xc040
	s_mov_b64 s[30:31], s[50:51]
	s_mov_b64 s[34:35], -1
	s_lshl_b32 s36, s25, 6
	s_mov_b32 s37, s36
	s_cmpk_gt_u32 s24, 0x187f
	s_cbranch_scc0 .Lcv_k3
	s_add_i32 s37, s24, 0xffffe780
	s_and_b32 s25, s37, 31
	s_lshr_b32 s26, s37, 5
	s_movk_i32 s27, 0x2000
	s_mov_b64 s[34:35], 0
	s_lshl_b32 s36, s25, 6
	s_mov_b32 s37, s36
	s_cmpk_gt_u32 s24, 0x1c7f
	s_cbranch_scc1 .Lcv_o3
	s_cmp_lt_u32 s25, 16
	s_cselect_b32 s28, s84, s86
	s_cselect_b32 s29, s85, s87
	s_add_u32 s28, s28, s2
	s_addc_u32 s29, s29, s3
	s_mov_b64 s[30:31], s[10:11]
	s_and_b32 s37, s25, 15
	s_lshl_b32 s37, s37, 6
	s_branch .Lcv_k3

; #define LDS_BARRIER() do { asm volatile("s_waitcnt lgkmcnt(0)" ::: "memory"); __builtin_amdgcn_s_barrier(); asm volatile("" ::: "memory"); } while (0)
; __device__ __forceinline__ u32x4 pack8(const float* v) { u32x4 o; o[0] = pk2(v[0], v[1]); o[1] = pk2(v[2], v[3]); o[2] = pk2(v[4], v[5]); o[3] = pk2(v[6], v[7]); return o; }
; __device__ __forceinline__ void tr_tile(const int tid, float* tile, const float* src, int ld, int k0, int j0, bool remap, bf16_t* dst, int ldd, int kd0) {
;     const int jj = tid & 63, kq = tid >> 6;
;     const int col = remap ? win_col(j0 + jj) : (j0 + jj);
; #pragma unroll
;     for (int i = 0; i < 8; ++i) { const int kk = kq + 8 * i; tile[kk * 65 + jj] = col >= 0 ? src[(size_t)(k0 + kk) * ld + col] : 0.f; }
;     LDS_BARRIER();
;     const int j = tid >> 3, pc = tid & 7; float v[8];
; #pragma unroll
;     for (int e = 0; e < 8; ++e) v[e] = tile[(pc * 8 + e) * 65 + j];
;     *(u32x4*)(dst + (size_t)(j0 + j) * ldd + kd0 + pc * 8) = pack8(v);
;     LDS_BARRIER();
; }
.Lcv_k3:
	s_mul_i32 s40, s37, s27
	s_add_u32 s28, s28, s40
	s_addc_u32 s29, s29, 0
	s_lshl_b32 s40, s36, 1
	s_add_u32 s30, s30, s40
	s_addc_u32 s31, s31, 0
	s_lshl_b32 s41, s26, 6
	s_lshl_b32 s42, s27, 3
	s_mov_b32 s43, 0
	v_add_u32_e32 v0, s41, v40
	v_add_u32_e32 v1, 16, v0
	v_cmp_gt_u32_e32 vcc, 0x1000, v0
	v_add_u32_e32 v2, 0xffffe000, v0
	v_mul_lo_u32 v3, v41, s27
	v_cndmask_b32_e32 v1, v1, v0, vcc
	v_cmp_gt_u32_e32 vcc, 0x3000, v0
	s_nop 1
	v_cndmask_b32_e32 v1, v2, v1, vcc
	v_cmp_gt_u32_e32 vcc, 0x3010, v0
	s_nop 1
	v_cndmask_b32_e32 v1, -1, v1, vcc
	v_cndmask_b32_e64 v1, v0, v1, s[34:35]
	v_lshl_add_u32 v136, v1, 2, v3
	v_lshl_add_u64 v[2:3], s[28:29], 0, v[136:137]
	v_cmp_le_i32_e32 vcc, 0, v1
	v_mov_b32_e32 v72, 0
	v_mov_b32_e32 v73, 0
	v_mov_b32_e32 v74, 0
	v_mov_b32_e32 v75, 0
	v_mov_b32_e32 v76, 0
	v_mov_b32_e32 v77, 0
	v_mov_b32_e32 v78, 0
	v_mov_b32_e32 v79, 0
	s_and_saveexec_b64 s[44:45], vcc
	global_load_dword v72, v[2:3], off
	v_lshl_add_u64 v[2:3], v[2:3], 0, s[42:43]
	global_load_dword v73, v[2:3], off
	v_lshl_add_u64 v[2:3], v[2:3], 0, s[42:43]
	global_load_dword v74, v[2:3], off
	v_lshl_add_u64 v[2:3], v[2:3], 0, s[42:43]
	global_load_dword v75, v[2:3], off
	v_lshl_add_u64 v[2:3], v[2:3], 0, s[42:43]
	global_load_dword v76, v[2:3], off
	v_lshl_add_u64 v[2:3], v[2:3], 0, s[42:43]
	global_load_dword v77, v[2:3], off
	v_lshl_add_u64 v[2:3], v[2:3], 0, s[42:43]
	global_load_dword v78, v[2:3], off
	v_lshl_add_u64 v[2:3], v[2:3], 0, s[42:43]
	global_load_dword v79, v[2:3], off
	s_mov_b64 exec, s[44:45]
	s_lshl_b32 s40, s41, 12
	v_add_u32_e32 v136, s40, v46
	v_lshl_add_u64 v[118:119], s[30:31], 0, v[136:137]
.Lcv_skip3:
	s_add_i32 s21, s21, s80
	s_waitcnt vmcnt(0)
	ds_write_b32 v44, v48
	ds_write_b32 v44, v49 offset:2080
	ds_write_b32 v44, v50 offset:4160
	ds_write_b32 v44, v51 offset:6240
	ds_write_b32 v44, v52 offset:8320
	ds_write_b32 v44, v53 offset:10400
	ds_write_b32 v44, v54 offset:12480
	ds_write_b32 v44, v55 offset:14560
	ds_write_b32 v44, v56 offset:16640
	ds_write_b32 v44, v57 offset:18720
	ds_write_b32 v44, v58 offset:20800
	ds_write_b32 v44, v59 offset:22880
	ds_write_b32 v44, v60 offset:24960
	ds_write_b32 v44, v61 offset:27040
	ds_write_b32 v44, v62 offset:29120
	ds_write_b32 v44, v63 offset:31200
	ds_write_b32 v44, v64 offset:33280
	ds_write_b32 v44, v65 offset:35360
	ds_write_b32 v44, v66 offset:37440
	ds_write_b32 v44, v67 offset:39520
	ds_write_b32 v44, v68 offset:41600
	ds_write_b32 v44, v69 offset:43680
	ds_write_b32 v44, v70 offset:45760
	ds_write_b32 v44, v71 offset:47840
	ds_write_b32 v44, v72 offset:49920
	ds_write_b32 v44, v73 offset:52000
	ds_write_b32 v44, v74 offset:54080
	ds_write_b32 v44, v75 offset:56160
	ds_write_b32 v44, v76 offset:58240
	ds_write_b32 v44, v77 offset:60320
	ds_write_b32 v44, v78 offset:62400
	ds_write_b32 v44, v79 offset:64480
	s_waitcnt lgkmcnt(0)
	s_barrier
	ds_read2_b32 v[48:49], v144 offset1:65
	ds_read2_b32 v[50:51], v144 offset0:130 offset1:195
	ds_read2_b32 v[52:53], v145 offset0:4 offset1:69
	ds_read2_b32 v[54:55], v145 offset0:134 offset1:199
	ds_read2_b32 v[56:57], v146 offset1:65
	ds_read2_b32 v[58:59], v146 offset0:130 offset1:195
	ds_read2_b32 v[60:61], v147 offset0:4 offset1:69
	ds_read2_b32 v[62:63], v147 offset0:134 offset1:199
	ds_read2_b32 v[64:65], v148 offset1:65
	ds_read2_b32 v[66:67], v148 offset0:130 offset1:195
	ds_read2_b32 v[68:69], v149 offset0:4 offset1:69
	ds_read2_b32 v[70:71], v149 offset0:134 offset1:199
	ds_read2_b32 v[72:73], v150 offset1:65
	ds_read2_b32 v[74:75], v150 offset0:130 offset1:195
	ds_read2_b32 v[76:77], v151 offset0:4 offset1:69
	ds_read2_b32 v[78:79], v151 offset0:134 offset1:199
	s_waitcnt lgkmcnt(12)
	v_cvt_pk_bf16_f32 v48, v48, v49
	v_cvt_pk_bf16_f32 v49, v50, v51
	v_cvt_pk_bf16_f32 v50, v52, v53
	v_cvt_pk_bf16_f32 v51, v54, v55
	s_bitcmp1_b32 s46, 0
	s_cbranch_scc0 .Lcv_nost0
	global_store_dwordx4 v[112:113], v[48:51], off
.Lcv_nost0:
	s_waitcnt lgkmcnt(8)
	v_cvt_pk_bf16_f32 v56, v56, v57
	v_cvt_pk_bf16_f32 v57, v58, v59
	v_cvt_pk_bf16_f32 v58, v60, v61
	v_cvt_pk_bf16_f32 v59, v62, v63
	s_bitcmp1_b32 s46, 1
	s_cbranch_scc0 .Lcv_nost1
	global_store_dwordx4 v[114:115], v[56:59], off
.Lcv_nost1:
	s_waitcnt lgkmcnt(4)
	v_cvt_pk_bf16_f32 v64, v64, v65
	v_cvt_pk_bf16_f32 v65, v66, v67
	v_cvt_pk_bf16_f32 v66, v68, v69
	v_cvt_pk_bf16_f32 v67, v70, v71
	s_bitcmp1_b32 s46, 2
	s_cbranch_scc0 .Lcv_nost2
	global_store_dwordx4 v[116:117], v[64:67], off
.Lcv_nost2:
	s_waitcnt lgkmcnt(0)
	v_cvt_pk_bf16_f32 v72, v72, v73
	v_cvt_pk_bf16_f32 v73, v74, v75
	v_cvt_pk_bf16_f32 v74, v76, v77
	v_cvt_pk_bf16_f32 v75, v78, v79
	s_bitcmp1_b32 s46, 3
	s_cbranch_scc0 .Lcv_nost3
	global_store_dwordx4 v[118:119], v[72:75], off
.Lcv_nost3:
	s_barrier
	s_mov_b32 s20, s21
	s_cmp_ge_i32 s20, s17
	s_cbranch_scc0 .Lcv_loop
	s_branch .LBB0_831
